# branch epilogue+hook loads batched, attention epilogue loads batched, prep jobs re-dealt and split across branch/Wo phases
# speedup vs baseline: 1.0225x; 1.0225x over previous
; #define LAS __attribute__((address_space(3)))
; __device__ __forceinline__ unsigned xb_add(unsigned* p, unsigned v) { return __hip_atomic_fetch_add(p, v, __ATOMIC_RELAXED, __HIP_MEMORY_SCOPE_AGENT); }
; __device__ __forceinline__ unsigned xb_xcc_id() { return (unsigned)__builtin_amdgcn_s_getreg((3 << 11) | 20) & 0xFu; }
; template <int PMASK> __global__ void __launch_bounds__(512, 2) hybrid_mega(Params p_byval) {
;     extern __shared__ __attribute__((aligned(16))) unsigned char smem[];
;     cg::grid_group grid = cg::this_grid();
;     PP p0 = (PP)__builtin_amdgcn_kernarg_segment_ptr();
;     const int lo = p0->ph_lo, hi = p0->ph_hi;
;     {
;         volatile LAS unsigned* st = (volatile LAS unsigned*)((LAS unsigned char*)smem + 131072);
;         if (threadIdx.x == 0) { st[0] = 0u; st[1] = 0u; }
;         if (blockIdx.x == 0) { unsigned* bar = (unsigned*)(p0->ws + WS_BAR); for (int i = threadIdx.x; i < XCD_BAR_WORDS; i += 512) bar[i] = 0u; }
;         __syncthreads();
;     }
;     for (int ph = lo; ph < hi; ++ph) {
;         if (ph == lo + 1) { grid.sync();
;             if (threadIdx.x == 0) (void)xb_add(&((unsigned*)(p0->ws + WS_BAR))[XB_XCNT(xb_xcc_id())], 1u); }
;         else if (ph > lo) { PP pb = p0; asm volatile("" : "+s"(pb)); xcd_barrier((unsigned*)(pb->ws + WS_BAR), (volatile LAS unsigned*)((LAS unsigned char*)smem + 131072)); }
;         PP p = p0; asm volatile("" : "+s"(p));
;         run_phase<PMASK>(p, ph, smem);
.LBB0_11:
	s_add_i32 s0, s48, 1
	v_lshrrev_b32_e32 v1, 20, v0
	v_lshrrev_b32_e32 v0, 10, v0
	v_writelane_b32 v249, s0, 4
	v_or_b32_e32 v0, v0, v1
	s_movk_i32 s0, 0x3ff
	v_and_or_b32 v0, v0, s0, v160
	s_lshl_b32 s0, s2, 6
	v_writelane_b32 v249, s0, 5
	s_ashr_i32 s0, s2, 6
	v_writelane_b32 v249, s0, 6
	s_add_i32 s0, s0, 15
	s_mul_hi_i32 s1, s0, 0x6000
	v_writelane_b32 v249, s1, 7
	s_mulk_i32 s0, 0x6000
	s_cmpk_lt_i32 s2, 0x9f0
	v_writelane_b32 v249, s0, 8
	s_cselect_b64 s[0:1], -1, 0
	v_writelane_b32 v249, s0, 9
	s_mov_b32 s35, 0
	s_movk_i32 s8, 0x1cc
	v_writelane_b32 v249, s1, 10
	s_ashr_i32 s0, s2, 31
	s_lshr_b32 s0, s0, 29
	s_add_i32 s0, s2, s0
	s_ashr_i32 s4, s0, 3
	s_and_b32 s0, s0, -8
	s_sub_i32 s5, s2, s0
	s_cmp_gt_i32 s2, 31
	s_cselect_b64 s[0:1], -1, 0
	v_writelane_b32 v249, s0, 11
	v_mbcnt_lo_u32_b32 v197, -1, 0
	s_mov_b32 s31, s48
	v_writelane_b32 v249, s1, 12
	s_sub_i32 s0, s2, 32
	s_sub_i32 s1, s3, 32
	v_writelane_b32 v249, s1, 13
	s_cmpk_lt_u32 s0, 0x9f0
	v_writelane_b32 v249, s0, 14
	s_cselect_b64 s[0:1], -1, 0
	v_writelane_b32 v249, s0, 15
	s_cmpk_lt_i32 s2, 0xa0
	s_movk_i32 s52, 0x6000
	v_writelane_b32 v249, s1, 16
	s_cselect_b64 s[0:1], -1, 0
	v_writelane_b32 v249, s0, 17
	s_lshl_b32 s54, s3, 9
	v_mov_b32_e32 v163, 0
	v_writelane_b32 v249, s1, 18
	s_mul_hi_i32 s0, s2, 0x66666667
	s_lshr_b32 s1, s0, 31
	s_ashr_i32 s0, s0, 1
	s_add_i32 s6, s0, s1
	s_mul_i32 s0, s6, -5
	s_add_i32 s1, s0, s2
	s_mul_i32 s0, s6, 0x500
	v_writelane_b32 v249, s1, 19
	s_lshl_b32 s1, s1, 8
	s_add_i32 s0, s1, s0
	s_ashr_i32 s1, s0, 31
	s_lshl_b64 s[0:1], s[0:1], 10
	v_writelane_b32 v249, s0, 20
	s_ashr_i32 s7, s6, 31
	s_movk_i32 s59, 0xff
	v_writelane_b32 v249, s1, 21
	s_lshl_b64 s[0:1], s[6:7], 18
	v_writelane_b32 v249, s0, 22
	v_mov_b32_e32 v161, 0x1000
	v_mov_b32_e32 v190, 0x2000
	v_writelane_b32 v249, s1, 23
	s_not_b32 s0, s2
	s_add_i32 s0, s3, s0
	s_lshl_b32 s0, s0, 9
	v_writelane_b32 v249, s0, 24
	s_lshl_b32 s0, s2, 3
	v_writelane_b32 v249, s0, 25
	s_lshl_b32 s0, s3, 3
	v_writelane_b32 v249, s0, 26
	s_lshl_b32 s0, s2, 9
	v_writelane_b32 v249, s0, 27
	s_mov_b32 s0, s6
	v_writelane_b32 v249, s0, 28
	v_mov_b32_e32 v191, 0x4fe9b000
	v_mov_b32_e32 v192, 1
	v_writelane_b32 v249, s1, 29
	s_lshl_b64 s[0:1], s[6:7], 17
	v_writelane_b32 v249, s0, 30
	s_cmpk_lt_i32 s2, 0xee0
	v_mov_b32_e32 v193, 0x4fe98000
	v_writelane_b32 v249, s1, 31
	s_cselect_b64 s[0:1], -1, 0
	v_writelane_b32 v249, s0, 32
	s_cmpk_gt_i32 s2, 0xe57
	s_movk_i32 s91, 0x2000
	v_writelane_b32 v249, s1, 33
	s_cselect_b64 s[0:1], -1, 0
	v_writelane_b32 v249, s0, 34
	s_movk_i32 s63, 0x800
	v_mov_b32_e32 v194, 0x358637bd
	v_writelane_b32 v249, s1, 35
	s_and_b32 s1, s2, 1
	s_add_i32 s0, s2, 0xfffff1a8
	v_writelane_b32 v249, s1, 36
	s_lshl_b32 s1, s1, 20
	s_lshr_b32 s0, s0, 1
	v_writelane_b32 v249, s1, 37
	s_mov_b32 s1, s35
	s_cmp_lt_i32 s5, 0
	v_writelane_b32 v249, s0, 38
	s_cselect_b64 s[6:7], -1, 0
	s_mov_b32 s64, 0x800000
	v_writelane_b32 v249, s1, 39
	v_writelane_b32 v249, s6, 40
	s_and_b64 s[0:1], s[6:7], exec
	s_cselect_b32 s0, s8, 0x1cb
	s_mul_i32 s0, s0, s5
	v_writelane_b32 v249, s7, 41
	s_add_i32 s0, s0, s4
	v_writelane_b32 v249, s5, 42
	s_mul_hi_i32 s1, s0, 0x4bda12f7
	v_writelane_b32 v249, s4, 43
	s_lshr_b32 s4, s1, 31
	s_ashr_i32 s1, s1, 6
	s_add_i32 s1, s1, s4
	s_lshl_b32 s4, s1, 2
	s_mulk_i32 s1, 0xd8
	s_sub_i32 s0, s0, s1
	s_bfe_u32 s1, s0, 0x2001d
	s_add_i32 s1, s0, s1
	s_sext_i32_i16 s5, s1
	s_and_b32 s1, s1, 0xfffc
	s_sub_i32 s1, s0, s1
	s_sext_i32_i16 s1, s1
	s_add_i32 s6, s4, s1
	s_ashr_i32 s1, s5, 2
	s_add_i32 s4, s1, 2
	s_cmp_gt_i32 s0, 15
	s_cselect_b32 s0, s4, s1
	s_ashr_i32 s1, s0, 31
	v_writelane_b32 v249, s0, 44
	s_ashr_i32 s7, s6, 31
	s_add_i32 s65, s48, -1
	v_writelane_b32 v249, s1, 45
	s_lshl_b32 s0, s2, 2
	v_writelane_b32 v249, s0, 46
	s_add_i32 s0, 0, 0x20000
	v_writelane_b32 v249, s0, 47
	s_add_i32 s0, 0, 0x20004
	v_writelane_b32 v249, s0, 48
	s_add_i32 s0, 0, 0x2000
	v_writelane_b32 v249, s0, 49
	s_add_i32 s0, 0, 0x8400
	v_writelane_b32 v249, s0, 50
	s_add_i32 s0, 0, 0x4400
	v_writelane_b32 v249, s0, 51
	v_cmp_eq_u32_e64 s[0:1], 0, v0
	v_mov_b32_e32 v195, 0x3c0881c4
	v_mov_b32_e32 v196, 0xbab64f3b
	v_writelane_b32 v249, s0, 52
	v_mbcnt_hi_u32_b32 v198, -1, v197
	v_mov_b32_e32 v199, 0x7f800000
	v_writelane_b32 v249, s1, 53
	s_mov_b32 s0, s6
	v_writelane_b32 v249, s0, 54
	v_not_b32_e32 v200, 63
	v_not_b32_e32 v201, 31
	v_writelane_b32 v249, s1, 55
	s_lshl_b64 s[0:1], s[6:7], 20
	v_writelane_b32 v249, s0, 56
	v_mov_b32_e32 v202, 0x7fc00000
	v_mov_b32_e32 v203, 0xffffff80
	v_writelane_b32 v249, s1, 57
	v_writelane_b32 v249, s46, 58
	v_mov_b32_e32 v204, 0x4000
	v_mov_b64_e32 v[164:165], 0x364
	v_writelane_b32 v249, s47, 59
	v_writelane_b32 v249, s48, 60
	v_mov_b32_e32 v205, 0xf149f2ca
	v_mov_b32_e32 v206, 0x100
	v_mov_b32_e32 v207, 0xff
	v_mov_b32_e32 v208, 0xfff
	s_mov_b32 s29, 0xe000
	s_movk_i32 s97, 0xa00
	s_movk_i32 s71, 0xff00
	s_movk_i32 s74, 0x1000
	s_movk_i32 s75, 0x7f
	s_mov_b32 s76, 0x3fb8aa3b
	s_mov_b32 s77, 0xc2ce8ed0
	s_mov_b32 s78, 0x42b17218
	s_brev_b32 s79, 18
	s_mov_b32 s33, 0xfe5163ab
	s_mov_b32 s56, 0x3c439041
	s_mov_b32 s70, 0xdb629599
	s_mov_b32 s88, 0xf534ddc0
	s_mov_b32 s89, 0xfc2757d1
	s_mov_b32 s57, 0x4e441529
	s_mov_b32 s26, 0xa2f9836e
	s_mov_b32 s30, 0x3fc90fda
	s_mov_b32 s27, 0x3f22f983
	s_mov_b32 s90, 0xbfc90fda
	s_brev_b32 s53, 1
	s_movk_i32 s36, 0x1f8
	s_movk_i32 s96, 0x440
	s_movk_i32 s58, 0x3c0
	s_movk_i32 s5, 0x5ff
	s_movk_i32 s80, 0x17f
	s_mov_b32 s81, 0xc400
	s_movk_i32 s66, 0x3dff
	s_movk_i32 s67, 0x1dff
	s_movk_i32 s28, 0x1fff
	s_movk_i32 s37, 0x25ff
	s_movk_i32 s44, 0x7bf
	s_movk_i32 s68, 0x7000
	s_movk_i32 s69, 0x7fff
	s_mov_b64 s[72:73], 0x80
	s_mov_b64 s[82:83], 0x800
	s_mov_b64 s[84:85], 0x60000
	s_mov_b64 s[86:87], 0x180000
	s_mov_b64 s[92:93], 0x4000
	s_mov_b64 s[94:95], 0x1c000
	v_writelane_b32 v249, s49, 61
	v_writelane_b32 v249, s54, 62
	s_mov_b32 s0, 0
	s_nop 0
	v_writelane_b32 v248, s0, 62
	s_branch .LBB0_13

; template <int PMASK> __device__ __forceinline__ void run_phase(PP p, int ph, unsigned char* smem) {
;     ...
;         if (layer < 3 && c >= 32) { __syncthreads(); prep_layer_jobs(p, smem, layer + 1, c - 32, G - 32, 0, 2544); } } break;
;     case 7: if constexpr ((PMASK >> 7) & 1) { OrderSimple S{ws + WS_MRG, ws + WS_WOT + (size_t)layer * DM * DM * 2, layer == 3 ? 64 : 68, 8, DM, DM, G, c};
;         EpiWo Ep{(bf16_t*)(p->ws + WS_Y)};
;         pg8::gemm_phase(lds, pg8::Gemm{DM, DM, DM}, S, Ep);
;         if (layer < 3 && c >= 32) { __syncthreads(); prep_layer_jobs(p, smem, layer + 1, c - 32, G - 32, 2544, 2544); } } break;
.LBB0_117:
	s_mov_b32 s4, s12
	v_writelane_b32 v249, s4, 63
	s_cmp_gt_i32 s12, 2
	v_readlane_b32 s8, v249, 11
	v_readlane_b32 s9, v249, 12
	s_cselect_b64 s[6:7], -1, 0
	s_xor_b64 s[8:9], s[8:9], -1
	s_or_b64 s[6:7], s[8:9], s[6:7]
	s_and_b64 vcc, exec, s[6:7]
	v_writelane_b32 v248, s5, 0
	s_cbranch_vccnz .LBB0_119
	s_waitcnt vmcnt(0) lgkmcnt(0)
	s_barrier
	s_mov_b32 s4, 1
	s_nop 0
	v_writelane_b32 v248, s4, 62
	s_mov_b64 s[6:7], -1
	s_branch .LBB0_120

; #define LAS __attribute__((address_space(3)))
; __device__ __forceinline__ int opaque_tid() { int t = threadIdx.x; asm volatile("" : "+v"(t)); return t; }
; #define PG8_STAGE(bufoff, gbase, voff) do { _Pragma("unroll") for (int _i = 0; _i < 2; ++_i) \
;         __builtin_amdgcn_global_load_lds((const unsigned*)((const char*)(gbase) + (voff)[_i]), (LAS unsigned*)(lds + (bufoff) + ldsw + _i * 8192), 16, 0, 0); } while (0)
; #define PG8_WAIT_V(n) asm volatile("s_waitcnt vmcnt(0)" ::: "memory")
; #define PG8_WAIT_V(n) asm volatile("s_waitcnt vmcnt(" #n ")" ::: "memory")
; #define PG8_BAR do { __builtin_amdgcn_sched_barrier(0); __builtin_amdgcn_s_barrier(); __builtin_amdgcn_sched_barrier(0); } while (0)
; template <class Epi, class Sched>
; __device__ __forceinline__ void gemm_phase(LAS unsigned char* lds, const Gemm g, const Sched& S, const Epi& E) {
;     const int tid = opaque_tid(), wid = __builtin_amdgcn_readfirstlane(tid >> 6), lane = tid & 63, wr = wid >> 2, wc = wid & 3, fr = lane & 15, fq = lane >> 4;
;     int K = g.K; asm volatile("" : "+s"(K)); const int nt = K / BK;
;     unsigned voffA[2], voffB[2];
; #pragma unroll
;     for (int i = 0; i < 2; ++i) { int R, C; stage_rc(tid * 16 + i * 8192, R, C); const int Rb = Epi::PERM ? ((R & ~31) + perm32(R & 31)) : R;
;         voffA[i] = (unsigned)(R * g.lda + C) * 2u; voffB[i] = (unsigned)(Rb * g.ldb + C) * 2u; }
;     const size_t kstep = (size_t)(BK * 2);
;     const size_t hstepA = (size_t)HALF * g.lda * 2, hstepB = (size_t)HALF * g.ldb * 2;
;     const unsigned ldsw = (unsigned)wid * 1024u;
;     const int aoff = lds_byte(wr * 64 + fr, fq * 8), boff = lds_byte(wc * 32 + fr, fq * 8);
;     ...
;     const char* cA = cur.a; const char* cB = cur.b;
;     PG8_STAGE(PG8_SB(0, 0), cB, voffB); PG8_STAGE(PG8_SA(0, 0), cA, voffA); PG8_STAGE(PG8_SB(0, 1), cB + hstepB, voffB); PG8_STAGE(PG8_SA(0, 1), cA + hstepA, voffA);
;     if (wr == 1) PG8_BAR;
;     PG8_WAIT_V(4); PG8_BAR;
;     PG8_STAGE(PG8_SB(1, 0), cB + kstep, voffB); PG8_STAGE(PG8_SA(1, 0), cA + kstep, voffA); PG8_STAGE(PG8_SB(1, 1), cB + hstepB + kstep, voffB);
.LBB0_120:
	s_and_b64 vcc, exec, s[6:7]
	v_writelane_b32 v248, s65, 9
	s_cbranch_vccz .LBB0_302
	s_load_dwordx2 s[6:7], s[0:1], 0xd0
	v_readlane_b32 s10, v249, 63
	v_mov_b32_e32 v11, v160
	s_movk_i32 s8, 0x800
	s_waitcnt lgkmcnt(0)
	s_add_u32 s14, s6, 0xe000000
	s_addc_u32 s15, s7, 0
	s_cmp_eq_u32 s10, 3
	s_cselect_b32 s41, 64, 0x44
	s_lshl_b32 s48, s41, 3
	v_readfirstlane_b32 s16, v11
	v_readlane_b32 vcc_lo, v248, 62
	s_cmp_lg_u32 vcc_lo, 0
	s_cselect_b32 s48, 0, s48
	s_cmp_ge_i32 s2, s48
	v_readlane_b32 s11, v248, 0
	s_cbranch_scc1 .LBB0_138
	v_lshlrev_b32_e32 v0, 4, v11
	v_add_u32_e32 v1, 0x2000, v0
	v_ashrrev_i32_e32 v2, 31, v1
	v_lshrrev_b32_e32 v2, 22, v2
	v_add_u32_e32 v2, v1, v2
	v_ashrrev_i32_e32 v8, 10, v2
	v_mul_i32_i24_e32 v2, 0x400, v8
	v_sub_u32_e32 v1, v1, v2
	v_lshrrev_b32_e32 v2, 4, v1
	v_bitop3_b32 v1, v2, v1, 32 bitop3:0x6c
	v_ashrrev_i32_e32 v2, 31, v1
	v_lshrrev_b32_e32 v2, 26, v2
	v_add_u32_e32 v2, v1, v2
	v_lshlrev_b32_e32 v3, 3, v8
	s_mov_b32 s4, s10
	v_ashrrev_i32_e32 v9, 6, v2
	v_and_b32_e32 v3, -16, v3
	v_writelane_b32 v249, s4, 63
	v_add_u32_e32 v3, v9, v3
	v_and_b32_e32 v4, 3, v9
	v_writelane_b32 v248, s5, 0
	s_mov_b32 s4, 0xfffe0
	v_lshrrev_b32_e32 v5, 2, v3
	v_lshlrev_b32_e32 v6, 1, v3
	v_and_b32_e32 v2, 0xc0, v2
	v_and_or_b32 v4, v3, s4, v4
	v_and_b32_e32 v5, 4, v5
	v_and_b32_e32 v6, 24, v6
	v_sub_u32_e32 v1, v1, v2
	v_or3_b32 v4, v4, v5, v6
	v_lshlrev_b32_e32 v5, 5, v8
	v_ashrrev_i16_sdwa v1, v192, sext(v1) dst_sel:DWORD dst_unused:UNUSED_PAD src0_sel:DWORD src1_sel:BYTE_0
	v_and_b32_e32 v5, 32, v5
	v_bfe_i32 v10, v1, 0, 16
	v_add_lshl_u32 v1, v5, v10, 1
	v_lshl_add_u32 v166, v4, 12, v1
	v_lshl_add_u32 v168, v3, 12, v1
	v_bfe_i32 v1, v11, 27, 1
	v_lshrrev_b32_e32 v1, 22, v1
	v_add_u32_e32 v1, v0, v1
	v_and_b32_e32 v1, 0xfffffc00, v1
	s_load_dwordx2 s[6:7], s[0:1], 0xd0
	v_sub_u32_e32 v0, v0, v1
	v_lshrrev_b32_e32 v1, 4, v0
	v_bitop3_b32 v1, v1, v0, 32 bitop3:0x6c
	v_ashrrev_i32_e32 v0, 31, v0
	v_lshrrev_b32_e32 v0, 26, v0
	v_add_u32_e32 v0, v1, v0
	s_waitcnt lgkmcnt(0)
	s_add_u32 s49, s6, 0x3e698000
	v_ashrrev_i32_e32 v12, 6, v0
	v_ashrrev_i32_e32 v0, 31, v11
	s_addc_u32 s50, s7, 0
	s_ashr_i32 s11, s10, 31
	v_lshrrev_b32_e32 v0, 26, v0
	s_lshl_b64 s[6:7], s[10:11], 23
	v_add_u32_e32 v0, v11, v0
	s_add_u32 s51, s14, s6
	v_ashrrev_i32_e32 v13, 6, v0
	s_addc_u32 s55, s15, s7
	s_ashr_i32 s10, s16, 6
	v_lshlrev_b32_e32 v0, 3, v13
	v_readlane_b32 s6, v249, 40
	s_ashr_i32 s9, s16, 8
	s_lshl_b32 s60, s10, 10
	v_and_b32_e32 v0, -16, v0
	s_or_b32 s61, s41, 1
	v_readlane_b32 s7, v249, 41
	v_add_u32_e32 v0, v12, v0
	v_and_b32_e32 v2, 3, v12
	s_and_b64 s[6:7], s[6:7], exec
	v_and_or_b32 v2, v0, s4, v2
	s_cselect_b32 s4, s61, s41
	v_readlane_b32 s6, v249, 42
	s_mul_i32 s4, s4, s6
	v_readlane_b32 s6, v249, 43
	s_add_i32 s4, s4, s6
	s_ashr_i32 s6, s4, 31
	v_lshrrev_b32_e32 v3, 2, v0
	v_lshlrev_b32_e32 v4, 1, v0
	s_lshr_b32 s6, s6, 27
	v_and_b32_e32 v3, 4, v3
	v_and_b32_e32 v4, 24, v4
	s_add_i32 s6, s4, s6
	v_or3_b32 v2, v2, v3, v4
	v_mul_i32_i24_e32 v4, 64, v12
	s_ashr_i32 s7, s6, 5
	v_sub_u32_e32 v1, v1, v4
	s_lshl_b32 s11, s7, 2
	v_lshlrev_b32_e32 v3, 5, v13
	v_ashrrev_i16_sdwa v1, v192, sext(v1) dst_sel:DWORD dst_unused:UNUSED_PAD src0_sel:DWORD src1_sel:BYTE_0
	s_sub_i32 s7, s41, s11
	v_and_b32_e32 v3, 32, v3
	v_bfe_i32 v14, v1, 0, 16
	s_min_u32 s12, s7, 4
	s_andn2_b32 s6, s6, 31
	v_add_lshl_u32 v1, v3, v14, 1
	s_sub_i32 s4, s4, s6
	v_cvt_f32_ubyte0_e32 v3, s12
	v_lshl_add_u32 v162, v2, 12, v1
	v_cvt_f32_i32_e32 v2, s4
	v_rcp_iflag_f32_e32 v4, v3
	v_lshl_add_u32 v170, v0, 12, v1
	s_ashr_i32 s6, s4, 30
	s_or_b32 s13, s6, 1
	v_mul_f32_e32 v0, v2, v4
	v_trunc_f32_e32 v0, v0
	v_fma_f32 v1, -v0, v3, v2
	v_cvt_i32_f32_e32 v0, v0
	v_cmp_ge_f32_e64 s[6:7], |v1|, v3
	s_and_b64 s[6:7], s[6:7], exec
	s_cselect_b32 s6, s13, 0
	v_readfirstlane_b32 s7, v0
	s_add_i32 s6, s7, s6
	s_mul_i32 s7, s6, s12
	s_sub_i32 s4, s4, s7
	s_sext_i32_i8 s4, s4
	s_add_i32 s20, s11, s4
	s_ashr_i32 s21, s20, 31
	s_lshl_b64 s[12:13], s[20:21], 20
	s_add_u32 s24, s49, s12
	s_addc_u32 s25, s50, s13
	s_bfe_i64 s[12:13], s[6:7], 0x80000
	s_lshl_b64 s[12:13], s[12:13], 20
	s_add_u32 s38, s51, s12
	s_addc_u32 s39, s55, s13
	s_add_i32 s21, s60, 0
	s_add_i32 m0, s21, 0x10000
	s_add_i32 s4, s21, 0x2000
	global_load_lds_dwordx4 v162, s[38:39]
	s_add_i32 m0, s21, 0x12000
	s_add_u32 s12, s38, 0x80000
	global_load_lds_dwordx4 v166, s[38:39]
	s_mov_b32 m0, s21
	s_addc_u32 s13, s39, 0
	global_load_lds_dwordx4 v170, s[24:25]
	s_mov_b32 m0, s4
	v_mov_b32_e32 v167, v163
	global_load_lds_dwordx4 v168, s[24:25]
	s_add_i32 m0, s21, 0x14000
	v_mov_b32_e32 v171, v163
	global_load_lds_dwordx4 v162, s[12:13]
	s_add_i32 m0, s21, 0x16000
	v_mov_b32_e32 v169, v163
	global_load_lds_dwordx4 v166, s[12:13]
	s_add_u32 s12, s24, 0x80000
	s_addc_u32 s13, s25, 0
	s_add_i32 s62, s21, 0x4000
	s_mov_b32 m0, s62
	s_add_i32 s63, s21, 0x6000
	global_load_lds_dwordx4 v170, s[12:13]
	s_mov_b32 m0, s63
	v_writelane_b32 v248, s14, 6
	global_load_lds_dwordx4 v168, s[12:13]
	v_lshl_add_u64 v[6:7], s[38:39], 0, v[162:163]
	v_lshl_add_u64 v[4:5], s[38:39], 0, v[166:167]
	v_lshl_add_u64 v[2:3], s[24:25], 0, v[170:171]
	s_cmp_lg_u32 s9, 1
	v_lshl_add_u64 v[0:1], s[24:25], 0, v[168:169]
	v_writelane_b32 v248, s15, 7
	s_cbranch_scc1 .LBB0_124
	s_barrier

; __device__ __forceinline__ void unpack8(const u32x4 w, float (&f)[8]) { f[0] = bflo(w.x); f[1] = bfhi(w.x); f[2] = bflo(w.y); f[3] = bfhi(w.y); f[4] = bflo(w.z); f[5] = bfhi(w.z); f[6] = bflo(w.w); f[7] = bfhi(w.w); }
; __device__ __forceinline__ u32x4 pack8(const float (&f)[8]) { u32x4 w; w.x = cvt_pk_bf16(f[0], f[1]); w.y = cvt_pk_bf16(f[2], f[3]); w.z = cvt_pk_bf16(f[4], f[5]); w.w = cvt_pk_bf16(f[6], f[7]); return w; }
;     __device__ __forceinline__ void operator()(const Acc& acc, const Unit& u, int wr, int wc, int fr, int fq) const {
;         const int row0 = u.pm * 256 + wr * 64 + fr, col0 = u.pn * 256 + wc * 32 + 8 * fq;
;         const bf16_t* gbase = R + (size_t)3 * T * DM + (size_t)(u.pm * 8 + u.pn) * 65536 + (((wr * 4 + wc) * 64) + fr + 16 * fq) * 8;
; #pragma unroll
;         for (int ai = 0; ai < 2; ++ai)
; #pragma unroll
;             for (int m = 0; m < 4; ++m) { const int row = row0 + ai * 128 + m * 16;
; #pragma unroll
;                 for (int bj = 0; bj < 2; ++bj) { float ga[8], v[8]; unpack8(*(const u32x4*)(gbase + ((ai * 4 + m) * 2 + bj) * 4096), ga);
; #pragma unroll
;                     for (int e = 0; e < 4; ++e) { v[e] = acc[ai][bj][m][0][e] * ga[e]; v[4 + e] = acc[ai][bj][m][1][e] * ga[4 + e]; }
;                     *(u32x4*)(mrg + (size_t)row * DM + col0 + bj * 128) = pack8(v); } }
;     }
.LBB0_126:
	v_lshl_add_u64 v[128:129], v[172:173], 0, s[22:23]
	global_load_dwordx4 v[132:135], v[128:129], off
	s_mov_b64 s[22:23], 0x2000
	s_nop 0
	v_lshl_add_u64 v[130:131], v[128:129], 0, s[22:23]
	global_load_dwordx4 v[144:147], v[130:131], off
	s_mov_b64 s[22:23], 0x4000
	s_nop 0
	v_lshl_add_u64 v[130:131], v[128:129], 0, s[22:23]
	global_load_dwordx4 v[148:151], v[130:131], off
	s_mov_b64 s[22:23], 0x6000
	s_nop 0
	v_lshl_add_u64 v[130:131], v[128:129], 0, s[22:23]
	global_load_dwordx4 v[152:155], v[130:131], off
	s_mov_b64 s[22:23], 0x8000
	s_nop 0
	v_lshl_add_u64 v[130:131], v[128:129], 0, s[22:23]
	global_load_dwordx4 v[156:159], v[130:131], off
	s_mov_b64 s[22:23], 0xa000
	s_nop 0
	v_lshl_add_u64 v[130:131], v[128:129], 0, s[22:23]
	global_load_dwordx4 v[184:187], v[130:131], off
	s_mov_b64 s[22:23], 0xc000
	s_nop 0
	v_lshl_add_u64 v[130:131], v[128:129], 0, s[22:23]
	global_load_dwordx4 v[210:213], v[130:131], off
	s_mov_b64 s[22:23], 0xe000
	s_nop 0
	v_lshl_add_u64 v[130:131], v[128:129], 0, s[22:23]
	global_load_dwordx4 v[214:217], v[130:131], off
	s_mov_b64 s[22:23], 0x10000
	s_nop 0
	v_lshl_add_u64 v[130:131], v[128:129], 0, s[22:23]
	global_load_dwordx4 v[218:221], v[130:131], off
	s_mov_b64 s[22:23], 0x12000
	s_nop 0
	v_lshl_add_u64 v[130:131], v[128:129], 0, s[22:23]
	global_load_dwordx4 v[222:225], v[130:131], off
	s_mov_b64 s[22:23], 0x14000
	s_nop 0
	v_lshl_add_u64 v[130:131], v[128:129], 0, s[22:23]
	global_load_dwordx4 v[226:229], v[130:131], off
	s_mov_b64 s[22:23], 0x16000
	s_nop 0
	v_lshl_add_u64 v[130:131], v[128:129], 0, s[22:23]
	global_load_dwordx4 v[230:233], v[130:131], off
	s_mov_b64 s[22:23], 0x18000
	s_nop 0
	v_lshl_add_u64 v[130:131], v[128:129], 0, s[22:23]
	global_load_dwordx4 v[234:237], v[130:131], off
	s_mov_b64 s[22:23], 0x1a000
	s_nop 0
	v_lshl_add_u64 v[130:131], v[128:129], 0, s[22:23]
	global_load_dwordx4 v[238:241], v[130:131], off
	s_mov_b64 s[22:23], 0x1c000
	s_nop 0
	v_lshl_add_u64 v[130:131], v[128:129], 0, s[22:23]
	global_load_dwordx4 v[242:245], v[130:131], off
	s_mov_b64 s[22:23], 0x1e000
	s_nop 0
	v_lshl_add_u64 v[130:131], v[128:129], 0, s[22:23]
	global_load_dwordx4 v[204:207], v[130:131], off
	v_lshl_add_u32 v130, s20, 8, v178
	v_lshl_or_b32 v136, s45, 8, v180
	v_ashrrev_i32_e32 v131, 31, v130
	v_ashrrev_i32_e32 v137, 31, v136
	v_lshlrev_b64 v[138:139], 12, v[130:131]
	s_movk_i32 s11, 0x4000
	s_mov_b64 s[22:23], 0x80000
	s_mov_b32 s20, s12
	s_mov_b32 s45, s10
	s_mov_b64 s[38:39], s[16:17]
	s_mov_b64 s[24:25], s[14:15]
	s_waitcnt vmcnt(0)
	v_lshlrev_b32_e32 v140, 16, v132
	v_and_b32_e32 v141, 0xffff0000, v132
	v_pk_mul_f32 v[120:121], v[120:121], v[140:141]
	v_lshlrev_b32_e32 v140, 16, v134
	v_and_b32_e32 v141, 0xffff0000, v134
	v_pk_mul_f32 v[140:141], v[124:125], v[140:141]
	v_lshlrev_b32_e32 v124, 16, v133
	v_and_b32_e32 v125, 0xffff0000, v133
	v_pk_mul_f32 v[122:123], v[122:123], v[124:125]
	v_lshlrev_b32_e32 v124, 16, v135
	v_and_b32_e32 v125, 0xffff0000, v135
	v_pk_mul_f32 v[132:133], v[126:127], v[124:125]
	v_cvt_pk_bf16_f32 v124, v120, v121
	v_cvt_pk_bf16_f32 v125, v122, v123
	v_lshl_add_u64 v[120:121], s[6:7], 0, v[138:139]
	v_lshlrev_b64 v[122:123], 1, v[136:137]
	v_cvt_pk_bf16_f32 v126, v140, v141
	v_cvt_pk_bf16_f32 v127, v132, v133
	v_lshl_add_u64 v[120:121], v[120:121], 0, v[122:123]
	global_store_dwordx4 v[120:121], v[124:127], off
	s_nop 1
	v_add_co_u32_e32 v124, vcc, s91, v128
	s_nop 1
	v_addc_co_u32_e32 v125, vcc, 0, v129, vcc
	v_mov_b64_e32 v[124:125], v[144:145]
	v_mov_b64_e32 v[126:127], v[146:147]
	v_lshlrev_b32_e32 v132, 16, v124
	v_and_b32_e32 v133, 0xffff0000, v124
	v_pk_mul_f32 v[116:117], v[116:117], v[132:133]
	v_lshlrev_b32_e32 v132, 16, v126
	v_and_b32_e32 v133, 0xffff0000, v126
	v_pk_mul_f32 v[132:133], v[112:113], v[132:133]
	v_lshlrev_b32_e32 v112, 16, v125
	v_and_b32_e32 v113, 0xffff0000, v125
	v_pk_mul_f32 v[118:119], v[118:119], v[112:113]
	v_lshlrev_b32_e32 v112, 16, v127
	v_and_b32_e32 v113, 0xffff0000, v127
	v_pk_mul_f32 v[124:125], v[114:115], v[112:113]
	v_cvt_pk_bf16_f32 v112, v116, v117
	v_cvt_pk_bf16_f32 v113, v118, v119
	v_cvt_pk_bf16_f32 v114, v132, v133
	v_cvt_pk_bf16_f32 v115, v124, v125
	global_store_dwordx4 v[120:121], v[112:115], off offset:256
	s_nop 1
	v_or_b32_e32 v112, 16, v130
	v_ashrrev_i32_e32 v113, 31, v112
	v_lshlrev_b64 v[116:117], 12, v[112:113]
	v_add_co_u32_e32 v112, vcc, s11, v128
	s_mov_b32 s11, 0x8000
	s_nop 0
	v_addc_co_u32_e32 v113, vcc, 0, v129, vcc
	v_mov_b64_e32 v[112:113], v[148:149]
	v_mov_b64_e32 v[114:115], v[150:151]
	v_lshlrev_b32_e32 v118, 16, v112
	v_and_b32_e32 v119, 0xffff0000, v112
	v_pk_mul_f32 v[108:109], v[108:109], v[118:119]
	v_lshlrev_b32_e32 v118, 16, v114
	v_and_b32_e32 v119, 0xffff0000, v114
	v_pk_mul_f32 v[118:119], v[104:105], v[118:119]
	v_lshlrev_b32_e32 v104, 16, v113
	v_and_b32_e32 v105, 0xffff0000, v113
	v_pk_mul_f32 v[110:111], v[110:111], v[104:105]
	v_lshlrev_b32_e32 v104, 16, v115
	v_and_b32_e32 v105, 0xffff0000, v115
	v_pk_mul_f32 v[112:113], v[106:107], v[104:105]
	v_cvt_pk_bf16_f32 v104, v108, v109
	v_lshl_add_u64 v[108:109], s[6:7], 0, v[116:117]
	v_cvt_pk_bf16_f32 v105, v110, v111
	v_cvt_pk_bf16_f32 v106, v118, v119
	v_cvt_pk_bf16_f32 v107, v112, v113
	v_lshl_add_u64 v[108:109], v[108:109], 0, v[122:123]
	global_store_dwordx4 v[108:109], v[104:107], off
	s_nop 1
	v_add_co_u32_e32 v104, vcc, s52, v128
	s_nop 1
	v_addc_co_u32_e32 v105, vcc, 0, v129, vcc
	v_mov_b64_e32 v[104:105], v[152:153]
	v_mov_b64_e32 v[106:107], v[154:155]
	v_lshlrev_b32_e32 v110, 16, v104
	v_and_b32_e32 v111, 0xffff0000, v104
	v_pk_mul_f32 v[100:101], v[100:101], v[110:111]
	v_lshlrev_b32_e32 v110, 16, v106
; __device__ __forceinline__ void unpack8(const u32x4 w, float (&f)[8]) { f[0] = bflo(w.x); f[1] = bfhi(w.x); f[2] = bflo(w.y); f[3] = bfhi(w.y); f[4] = bflo(w.z); f[5] = bfhi(w.z); f[6] = bflo(w.w); f[7] = bfhi(w.w); }
; __device__ __forceinline__ u32x4 pack8(const float (&f)[8]) { u32x4 w; w.x = cvt_pk_bf16(f[0], f[1]); w.y = cvt_pk_bf16(f[2], f[3]); w.z = cvt_pk_bf16(f[4], f[5]); w.w = cvt_pk_bf16(f[6], f[7]); return w; }
;     __device__ __forceinline__ void operator()(const Acc& acc, const Unit& u, int wr, int wc, int fr, int fq) const {
;         const int row0 = u.pm * 256 + wr * 64 + fr, col0 = u.pn * 256 + wc * 32 + 8 * fq;
;         const bf16_t* gbase = R + (size_t)3 * T * DM + (size_t)(u.pm * 8 + u.pn) * 65536 + (((wr * 4 + wc) * 64) + fr + 16 * fq) * 8;
; #pragma unroll
;         for (int ai = 0; ai < 2; ++ai)
; #pragma unroll
;             for (int m = 0; m < 4; ++m) { const int row = row0 + ai * 128 + m * 16;
; #pragma unroll
;                 for (int bj = 0; bj < 2; ++bj) { float ga[8], v[8]; unpack8(*(const u32x4*)(gbase + ((ai * 4 + m) * 2 + bj) * 4096), ga);
; #pragma unroll
;                     for (int e = 0; e < 4; ++e) { v[e] = acc[ai][bj][m][0][e] * ga[e]; v[4 + e] = acc[ai][bj][m][1][e] * ga[4 + e]; }
;                     *(u32x4*)(mrg + (size_t)row * DM + col0 + bj * 128) = pack8(v); } }
;     }
	v_and_b32_e32 v111, 0xffff0000, v106
	v_pk_mul_f32 v[110:111], v[96:97], v[110:111]
	v_lshlrev_b32_e32 v96, 16, v105
	v_and_b32_e32 v97, 0xffff0000, v105
	v_pk_mul_f32 v[102:103], v[102:103], v[96:97]
	v_lshlrev_b32_e32 v96, 16, v107
	v_and_b32_e32 v97, 0xffff0000, v107
	v_pk_mul_f32 v[104:105], v[98:99], v[96:97]
	v_cvt_pk_bf16_f32 v96, v100, v101
	v_cvt_pk_bf16_f32 v97, v102, v103
	v_cvt_pk_bf16_f32 v98, v110, v111
	v_cvt_pk_bf16_f32 v99, v104, v105
	global_store_dwordx4 v[108:109], v[96:99], off offset:256
	s_nop 1
	v_or_b32_e32 v96, 32, v130
	v_ashrrev_i32_e32 v97, 31, v96
	v_lshlrev_b64 v[100:101], 12, v[96:97]
	v_add_co_u32_e32 v96, vcc, s11, v128
	s_mov_b32 s11, 0xa000
	s_nop 0
	v_addc_co_u32_e32 v97, vcc, 0, v129, vcc
	v_mov_b64_e32 v[96:97], v[156:157]
	v_mov_b64_e32 v[98:99], v[158:159]
	v_lshlrev_b32_e32 v102, 16, v96
	v_and_b32_e32 v103, 0xffff0000, v96
	v_pk_mul_f32 v[92:93], v[92:93], v[102:103]
	v_lshlrev_b32_e32 v102, 16, v98
	v_and_b32_e32 v103, 0xffff0000, v98
	v_pk_mul_f32 v[102:103], v[88:89], v[102:103]
	v_lshlrev_b32_e32 v88, 16, v97
	v_and_b32_e32 v89, 0xffff0000, v97
	v_pk_mul_f32 v[94:95], v[94:95], v[88:89]
	v_lshlrev_b32_e32 v88, 16, v99
	v_and_b32_e32 v89, 0xffff0000, v99
	v_pk_mul_f32 v[96:97], v[90:91], v[88:89]
	v_cvt_pk_bf16_f32 v88, v92, v93
	v_lshl_add_u64 v[92:93], s[6:7], 0, v[100:101]
	v_cvt_pk_bf16_f32 v89, v94, v95
	v_cvt_pk_bf16_f32 v90, v102, v103
	v_cvt_pk_bf16_f32 v91, v96, v97
	v_lshl_add_u64 v[92:93], v[92:93], 0, v[122:123]
	global_store_dwordx4 v[92:93], v[88:91], off
	s_nop 1
	v_add_co_u32_e32 v88, vcc, s11, v128
	s_mov_b32 s11, 0xc000
	s_nop 0
	v_addc_co_u32_e32 v89, vcc, 0, v129, vcc
	v_mov_b64_e32 v[88:89], v[184:185]
	v_mov_b64_e32 v[90:91], v[186:187]
	v_lshlrev_b32_e32 v94, 16, v88
	v_and_b32_e32 v95, 0xffff0000, v88
	v_pk_mul_f32 v[84:85], v[84:85], v[94:95]
	v_lshlrev_b32_e32 v94, 16, v90
	v_and_b32_e32 v95, 0xffff0000, v90
	v_pk_mul_f32 v[94:95], v[80:81], v[94:95]
	v_lshlrev_b32_e32 v80, 16, v89
	v_and_b32_e32 v81, 0xffff0000, v89
	v_pk_mul_f32 v[86:87], v[86:87], v[80:81]
	v_lshlrev_b32_e32 v80, 16, v91
	v_and_b32_e32 v81, 0xffff0000, v91
	v_pk_mul_f32 v[88:89], v[82:83], v[80:81]
	v_cvt_pk_bf16_f32 v80, v84, v85
	v_cvt_pk_bf16_f32 v81, v86, v87
	v_cvt_pk_bf16_f32 v82, v94, v95
	v_cvt_pk_bf16_f32 v83, v88, v89
	global_store_dwordx4 v[92:93], v[80:83], off offset:256
	s_nop 1
	v_or_b32_e32 v80, 48, v130
	v_ashrrev_i32_e32 v81, 31, v80
	v_lshlrev_b64 v[84:85], 12, v[80:81]
	v_add_co_u32_e32 v80, vcc, s11, v128
	s_mov_b32 s11, 0x10000
	s_nop 0
	v_addc_co_u32_e32 v81, vcc, 0, v129, vcc
	v_mov_b64_e32 v[80:81], v[210:211]
	v_mov_b64_e32 v[82:83], v[212:213]
	v_lshlrev_b32_e32 v86, 16, v80
	v_and_b32_e32 v87, 0xffff0000, v80
	v_pk_mul_f32 v[76:77], v[76:77], v[86:87]
	v_lshlrev_b32_e32 v86, 16, v82
	v_and_b32_e32 v87, 0xffff0000, v82
	v_pk_mul_f32 v[86:87], v[72:73], v[86:87]
	v_lshlrev_b32_e32 v72, 16, v81
	v_and_b32_e32 v73, 0xffff0000, v81
	v_pk_mul_f32 v[78:79], v[78:79], v[72:73]
	v_lshlrev_b32_e32 v72, 16, v83
	v_and_b32_e32 v73, 0xffff0000, v83
	v_pk_mul_f32 v[80:81], v[74:75], v[72:73]
	v_cvt_pk_bf16_f32 v72, v76, v77
	v_lshl_add_u64 v[76:77], s[6:7], 0, v[84:85]
	v_cvt_pk_bf16_f32 v73, v78, v79
	v_cvt_pk_bf16_f32 v74, v86, v87
	v_cvt_pk_bf16_f32 v75, v80, v81
	v_lshl_add_u64 v[76:77], v[76:77], 0, v[122:123]
	global_store_dwordx4 v[76:77], v[72:75], off
	s_nop 1
	v_add_co_u32_e32 v72, vcc, s29, v128
	s_nop 1
	v_addc_co_u32_e32 v73, vcc, 0, v129, vcc
	v_mov_b64_e32 v[72:73], v[214:215]
	v_mov_b64_e32 v[74:75], v[216:217]
	v_lshlrev_b32_e32 v78, 16, v72
	v_and_b32_e32 v79, 0xffff0000, v72
	v_pk_mul_f32 v[68:69], v[68:69], v[78:79]
	v_lshlrev_b32_e32 v78, 16, v74
	v_and_b32_e32 v79, 0xffff0000, v74
	v_pk_mul_f32 v[78:79], v[64:65], v[78:79]
	v_lshlrev_b32_e32 v64, 16, v73
	v_and_b32_e32 v65, 0xffff0000, v73
	v_pk_mul_f32 v[70:71], v[70:71], v[64:65]
	v_lshlrev_b32_e32 v64, 16, v75
	v_and_b32_e32 v65, 0xffff0000, v75
	v_pk_mul_f32 v[72:73], v[66:67], v[64:65]
	v_cvt_pk_bf16_f32 v64, v68, v69
	v_cvt_pk_bf16_f32 v65, v70, v71
	v_cvt_pk_bf16_f32 v66, v78, v79
	v_cvt_pk_bf16_f32 v67, v72, v73
	global_store_dwordx4 v[76:77], v[64:67], off offset:256
	s_nop 1
	v_add_co_u32_e32 v64, vcc, s11, v128
	s_mov_b32 s11, 0x80000
	s_nop 0
	v_addc_co_u32_e32 v65, vcc, 0, v129, vcc
	v_mov_b64_e32 v[64:65], v[218:219]
	v_mov_b64_e32 v[66:67], v[220:221]
	v_lshlrev_b32_e32 v68, 16, v64
	v_and_b32_e32 v69, 0xffff0000, v64
	v_pk_mul_f32 v[60:61], v[60:61], v[68:69]
	v_lshlrev_b32_e32 v68, 16, v66
	v_and_b32_e32 v69, 0xffff0000, v66
	v_pk_mul_f32 v[68:69], v[56:57], v[68:69]
	v_lshlrev_b32_e32 v56, 16, v65
	v_and_b32_e32 v57, 0xffff0000, v65
	v_pk_mul_f32 v[62:63], v[62:63], v[56:57]
	v_lshlrev_b32_e32 v56, 16, v67
	v_and_b32_e32 v57, 0xffff0000, v67
	v_pk_mul_f32 v[64:65], v[58:59], v[56:57]
	v_cvt_pk_bf16_f32 v57, v62, v63
	v_add_co_u32_e32 v62, vcc, s11, v120
	v_cvt_pk_bf16_f32 v56, v60, v61
	v_cvt_pk_bf16_f32 v58, v68, v69
	v_cvt_pk_bf16_f32 v59, v64, v65
	v_addc_co_u32_e32 v63, vcc, 0, v121, vcc
	s_mov_b32 s11, 0x12000
	global_store_dwordx4 v[62:63], v[56:59], off
	v_lshl_add_u64 v[60:61], v[120:121], 0, s[22:23]
	s_mov_b64 s[22:23], 0x90000
	v_add_co_u32_e32 v56, vcc, s11, v128
	s_mov_b32 s11, 0x14000
	s_nop 0
	v_addc_co_u32_e32 v57, vcc, 0, v129, vcc
	v_mov_b64_e32 v[56:57], v[222:223]
	v_mov_b64_e32 v[58:59], v[224:225]
	v_lshlrev_b32_e32 v62, 16, v56
	v_and_b32_e32 v63, 0xffff0000, v56
	v_pk_mul_f32 v[52:53], v[52:53], v[62:63]
	v_lshlrev_b32_e32 v62, 16, v58
	v_and_b32_e32 v63, 0xffff0000, v58
	v_pk_mul_f32 v[62:63], v[48:49], v[62:63]
	v_lshlrev_b32_e32 v48, 16, v57
	v_and_b32_e32 v49, 0xffff0000, v57
; __device__ __forceinline__ void unpack8(const u32x4 w, float (&f)[8]) { f[0] = bflo(w.x); f[1] = bfhi(w.x); f[2] = bflo(w.y); f[3] = bfhi(w.y); f[4] = bflo(w.z); f[5] = bfhi(w.z); f[6] = bflo(w.w); f[7] = bfhi(w.w); }
; __device__ __forceinline__ u32x4 pack8(const float (&f)[8]) { u32x4 w; w.x = cvt_pk_bf16(f[0], f[1]); w.y = cvt_pk_bf16(f[2], f[3]); w.z = cvt_pk_bf16(f[4], f[5]); w.w = cvt_pk_bf16(f[6], f[7]); return w; }
;     __device__ __forceinline__ void operator()(const Acc& acc, const Unit& u, int wr, int wc, int fr, int fq) const {
;         const int row0 = u.pm * 256 + wr * 64 + fr, col0 = u.pn * 256 + wc * 32 + 8 * fq;
;         const bf16_t* gbase = R + (size_t)3 * T * DM + (size_t)(u.pm * 8 + u.pn) * 65536 + (((wr * 4 + wc) * 64) + fr + 16 * fq) * 8;
; #pragma unroll
;         for (int ai = 0; ai < 2; ++ai)
; #pragma unroll
;             for (int m = 0; m < 4; ++m) { const int row = row0 + ai * 128 + m * 16;
; #pragma unroll
;                 for (int bj = 0; bj < 2; ++bj) { float ga[8], v[8]; unpack8(*(const u32x4*)(gbase + ((ai * 4 + m) * 2 + bj) * 4096), ga);
; #pragma unroll
;                     for (int e = 0; e < 4; ++e) { v[e] = acc[ai][bj][m][0][e] * ga[e]; v[4 + e] = acc[ai][bj][m][1][e] * ga[4 + e]; }
;                     *(u32x4*)(mrg + (size_t)row * DM + col0 + bj * 128) = pack8(v); } }
;     }
	v_pk_mul_f32 v[54:55], v[54:55], v[48:49]
	v_lshlrev_b32_e32 v48, 16, v59
	v_and_b32_e32 v49, 0xffff0000, v59
	v_pk_mul_f32 v[56:57], v[50:51], v[48:49]
	v_cvt_pk_bf16_f32 v48, v52, v53
	v_cvt_pk_bf16_f32 v49, v54, v55
	v_cvt_pk_bf16_f32 v50, v62, v63
	v_cvt_pk_bf16_f32 v51, v56, v57
	global_store_dwordx4 v[60:61], v[48:51], off offset:256
	s_nop 1
	v_add_co_u32_e32 v48, vcc, s11, v128
	s_mov_b32 s11, 0x90000
	s_nop 0
	v_addc_co_u32_e32 v49, vcc, 0, v129, vcc
	v_mov_b64_e32 v[48:49], v[226:227]
	v_mov_b64_e32 v[50:51], v[228:229]
	v_lshlrev_b32_e32 v52, 16, v48
	v_and_b32_e32 v53, 0xffff0000, v48
	v_pk_mul_f32 v[44:45], v[44:45], v[52:53]
	v_lshlrev_b32_e32 v52, 16, v50
	v_and_b32_e32 v53, 0xffff0000, v50
	v_pk_mul_f32 v[52:53], v[40:41], v[52:53]
	v_lshlrev_b32_e32 v40, 16, v49
	v_and_b32_e32 v41, 0xffff0000, v49
	v_pk_mul_f32 v[46:47], v[46:47], v[40:41]
	v_lshlrev_b32_e32 v40, 16, v51
	v_and_b32_e32 v41, 0xffff0000, v51
	v_pk_mul_f32 v[48:49], v[42:43], v[40:41]
	v_cvt_pk_bf16_f32 v41, v46, v47
	v_add_co_u32_e32 v46, vcc, s11, v120
	v_cvt_pk_bf16_f32 v40, v44, v45
	v_cvt_pk_bf16_f32 v42, v52, v53
	v_cvt_pk_bf16_f32 v43, v48, v49
	v_addc_co_u32_e32 v47, vcc, 0, v121, vcc
	s_mov_b32 s11, 0x16000
	global_store_dwordx4 v[46:47], v[40:43], off
	v_lshl_add_u64 v[44:45], v[120:121], 0, s[22:23]
	s_mov_b64 s[22:23], 0xa0000
	v_add_co_u32_e32 v40, vcc, s11, v128
	s_mov_b32 s11, 0x18000
	s_nop 0
	v_addc_co_u32_e32 v41, vcc, 0, v129, vcc
	v_mov_b64_e32 v[40:41], v[230:231]
	v_mov_b64_e32 v[42:43], v[232:233]
	v_lshlrev_b32_e32 v46, 16, v40
	v_and_b32_e32 v47, 0xffff0000, v40
	v_pk_mul_f32 v[36:37], v[36:37], v[46:47]
	v_lshlrev_b32_e32 v46, 16, v42
	v_and_b32_e32 v47, 0xffff0000, v42
	v_pk_mul_f32 v[46:47], v[32:33], v[46:47]
	v_lshlrev_b32_e32 v32, 16, v41
	v_and_b32_e32 v33, 0xffff0000, v41
	v_pk_mul_f32 v[38:39], v[38:39], v[32:33]
	v_lshlrev_b32_e32 v32, 16, v43
	v_and_b32_e32 v33, 0xffff0000, v43
	v_pk_mul_f32 v[40:41], v[34:35], v[32:33]
	v_cvt_pk_bf16_f32 v32, v36, v37
	v_cvt_pk_bf16_f32 v33, v38, v39
	v_cvt_pk_bf16_f32 v34, v46, v47
	v_cvt_pk_bf16_f32 v35, v40, v41
	global_store_dwordx4 v[44:45], v[32:35], off offset:256
	s_nop 1
	v_add_co_u32_e32 v32, vcc, s11, v128
	s_mov_b32 s11, 0xa0000
	s_nop 0
	v_addc_co_u32_e32 v33, vcc, 0, v129, vcc
	v_mov_b64_e32 v[32:33], v[234:235]
	v_mov_b64_e32 v[34:35], v[236:237]
	v_lshlrev_b32_e32 v36, 16, v32
	v_and_b32_e32 v37, 0xffff0000, v32
	v_pk_mul_f32 v[28:29], v[28:29], v[36:37]
	v_lshlrev_b32_e32 v36, 16, v34
	v_and_b32_e32 v37, 0xffff0000, v34
	v_pk_mul_f32 v[36:37], v[24:25], v[36:37]
	v_lshlrev_b32_e32 v24, 16, v33
	v_and_b32_e32 v25, 0xffff0000, v33
	v_pk_mul_f32 v[30:31], v[30:31], v[24:25]
	v_lshlrev_b32_e32 v24, 16, v35
	v_and_b32_e32 v25, 0xffff0000, v35
	v_pk_mul_f32 v[32:33], v[26:27], v[24:25]
	v_cvt_pk_bf16_f32 v25, v30, v31
	v_add_co_u32_e32 v30, vcc, s11, v120
	v_cvt_pk_bf16_f32 v24, v28, v29
	v_cvt_pk_bf16_f32 v26, v36, v37
	v_cvt_pk_bf16_f32 v27, v32, v33
	v_addc_co_u32_e32 v31, vcc, 0, v121, vcc
	s_mov_b32 s11, 0x1a000
	global_store_dwordx4 v[30:31], v[24:27], off
	v_lshl_add_u64 v[28:29], v[120:121], 0, s[22:23]
	s_mov_b64 s[22:23], 0xb0000
	v_add_co_u32_e32 v24, vcc, s11, v128
	s_mov_b32 s11, 0x1c000
	s_nop 0
	v_addc_co_u32_e32 v25, vcc, 0, v129, vcc
	v_mov_b64_e32 v[24:25], v[238:239]
	v_mov_b64_e32 v[26:27], v[240:241]
	v_lshlrev_b32_e32 v30, 16, v24
	v_and_b32_e32 v31, 0xffff0000, v24
	v_pk_mul_f32 v[20:21], v[20:21], v[30:31]
	v_lshlrev_b32_e32 v30, 16, v26
	v_and_b32_e32 v31, 0xffff0000, v26
	v_pk_mul_f32 v[30:31], v[16:17], v[30:31]
	v_lshlrev_b32_e32 v16, 16, v25
	v_and_b32_e32 v17, 0xffff0000, v25
	v_pk_mul_f32 v[22:23], v[22:23], v[16:17]
	v_lshlrev_b32_e32 v16, 16, v27
	v_and_b32_e32 v17, 0xffff0000, v27
	v_pk_mul_f32 v[24:25], v[18:19], v[16:17]
	v_cvt_pk_bf16_f32 v16, v20, v21
	v_cvt_pk_bf16_f32 v17, v22, v23
	v_cvt_pk_bf16_f32 v18, v30, v31
	v_cvt_pk_bf16_f32 v19, v24, v25
	global_store_dwordx4 v[28:29], v[16:19], off offset:256
	s_nop 1
	v_add_co_u32_e32 v16, vcc, s11, v128
	s_mov_b32 s11, 0xb0000
	s_nop 0
	v_addc_co_u32_e32 v17, vcc, 0, v129, vcc
	v_mov_b64_e32 v[16:17], v[242:243]
	v_mov_b64_e32 v[18:19], v[244:245]
	v_lshlrev_b32_e32 v20, 16, v16
	v_and_b32_e32 v21, 0xffff0000, v16
	v_pk_mul_f32 v[12:13], v[12:13], v[20:21]
	v_lshlrev_b32_e32 v20, 16, v18
	v_and_b32_e32 v21, 0xffff0000, v18
	v_pk_mul_f32 v[20:21], v[8:9], v[20:21]
	v_lshlrev_b32_e32 v8, 16, v17
	v_and_b32_e32 v9, 0xffff0000, v17
	v_pk_mul_f32 v[14:15], v[14:15], v[8:9]
	v_lshlrev_b32_e32 v8, 16, v19
	v_and_b32_e32 v9, 0xffff0000, v19
	v_pk_mul_f32 v[16:17], v[10:11], v[8:9]
	v_cvt_pk_bf16_f32 v9, v14, v15
	v_add_co_u32_e32 v14, vcc, s11, v120
	v_cvt_pk_bf16_f32 v8, v12, v13
	v_cvt_pk_bf16_f32 v10, v20, v21
	v_cvt_pk_bf16_f32 v11, v16, v17
	v_addc_co_u32_e32 v15, vcc, 0, v121, vcc
	s_mov_b32 s11, 0x1e000
	global_store_dwordx4 v[14:15], v[8:11], off
	v_lshl_add_u64 v[12:13], v[120:121], 0, s[22:23]
	s_nop 0
	v_add_co_u32_e32 v8, vcc, s11, v128
	s_nop 1
	v_addc_co_u32_e32 v9, vcc, 0, v129, vcc
	v_mov_b64_e32 v[8:9], v[204:205]
	v_mov_b64_e32 v[10:11], v[206:207]
	v_mov_b32_e32 v204, 0x4000
	v_mov_b32_e32 v205, 0xf149f2ca
	v_mov_b32_e32 v206, 0x100
	v_mov_b32_e32 v207, 0xff
	s_and_b64 vcc, exec, s[18:19]
	v_lshlrev_b32_e32 v14, 16, v8
	v_and_b32_e32 v15, 0xffff0000, v8
	v_pk_mul_f32 v[4:5], v[4:5], v[14:15]
	v_lshlrev_b32_e32 v14, 16, v10
	v_and_b32_e32 v15, 0xffff0000, v10
	v_pk_mul_f32 v[14:15], v[0:1], v[14:15]
	v_lshlrev_b32_e32 v0, 16, v9
	v_and_b32_e32 v1, 0xffff0000, v9
	v_pk_mul_f32 v[6:7], v[6:7], v[0:1]
	v_lshlrev_b32_e32 v0, 16, v11
	v_and_b32_e32 v1, 0xffff0000, v11
	v_pk_mul_f32 v[8:9], v[2:3], v[0:1]
	v_cvt_pk_bf16_f32 v0, v4, v5
	v_cvt_pk_bf16_f32 v1, v6, v7
	v_cvt_pk_bf16_f32 v2, v14, v15
	v_cvt_pk_bf16_f32 v3, v8, v9
	global_store_dwordx4 v[12:13], v[0:3], off offset:256
	s_cbranch_vccnz .LBB0_135

; __device__ __forceinline__ void unpack8(const u32x4 w, float (&f)[8]) { f[0] = bflo(w.x); f[1] = bfhi(w.x); f[2] = bflo(w.y); f[3] = bfhi(w.y); f[4] = bflo(w.z); f[5] = bfhi(w.z); f[6] = bflo(w.w); f[7] = bfhi(w.w); }
;     __device__ __forceinline__ void segment(Acc& acc, const Unit& u, int seg, int wr, int wc, int fr, int fq) const {
;         int loff = (((wr * 4 + wc) * 64) + fr + 16 * fq) * 8;
;         asm volatile("" : "+v"(loff));
;         const bf16_t* rbase = R + (size_t)(seg - 1) * T * DM + (size_t)(u.pm * 8 + u.pn) * 65536 + loff;
;         u32x4 rr[2][4][2];
; #pragma unroll
;         for (int ai = 0; ai < 2; ++ai)
; #pragma unroll
;             for (int m = 0; m < 4; ++m)
; #pragma unroll
;                 for (int bj = 0; bj < 2; ++bj) rr[ai][m][bj] = *(const u32x4*)(rbase + ((ai * 4 + m) * 2 + bj) * 4096);
; #pragma unroll
;         for (int ai = 0; ai < 2; ++ai)
; #pragma unroll
;             for (int m = 0; m < 4; ++m)
; #pragma unroll
;                 for (int bj = 0; bj < 2; ++bj) { float r[8]; unpack8(rr[ai][m][bj], r);
; #pragma unroll
;                     for (int e = 0; e < 4; ++e) { acc[ai][bj][m][0][e] *= r[e]; acc[ai][bj][m][1][e] *= r[4 + e]; } }
;         __builtin_amdgcn_sched_barrier(0);
;     }
.LBB0_131:
	s_cmp_eq_u32 s38, 0
	s_cselect_b64 s[42:43], -1, 0
	s_and_b32 s39, s38, 6
	s_cmp_lg_u32 s39, 0
	s_cselect_b64 s[96:97], -1, 0
	s_or_b64 s[42:43], s[42:43], s[96:97]
	s_and_b64 vcc, exec, s[42:43]
	s_cbranch_vccnz .LBB0_133
	s_lshr_b32 s39, s38, 3
	s_add_i32 s39, s39, -1
	s_mul_hi_i32 s43, s39, 0x4400000
	s_mul_i32 s39, s39, 0x4400000
	v_mov_b32_e32 v128, v181
	s_add_u32 s42, s11, s39
	s_addc_u32 s43, s13, s43
	v_ashrrev_i32_e32 v129, 31, v128
	v_lshl_add_u64 v[128:129], v[128:129], 1, s[42:43]
	global_load_dwordx4 v[184:187], v[128:129], off
	v_add_co_u32_e32 v130, vcc, s91, v128
	s_movk_i32 s39, 0x4000
	s_nop 0
	v_addc_co_u32_e32 v131, vcc, 0, v129, vcc
	global_load_dwordx4 v[210:213], v[130:131], off
	v_add_co_u32_e32 v130, vcc, s39, v128
	s_mov_b32 s39, 0x8000
	s_nop 0
	v_addc_co_u32_e32 v131, vcc, 0, v129, vcc
	v_add_co_u32_e32 v132, vcc, s52, v128
	s_nop 0
	s_nop 0
	v_addc_co_u32_e32 v133, vcc, 0, v129, vcc
	global_load_dwordx4 v[214:217], v[130:131], off
	global_load_dwordx4 v[218:221], v[132:133], off
	v_add_co_u32_e32 v130, vcc, s39, v128
	s_mov_b32 s39, 0xa000
	s_nop 0
	v_addc_co_u32_e32 v131, vcc, 0, v129, vcc
	v_add_co_u32_e32 v132, vcc, s39, v128
	s_mov_b32 s39, 0xc000
	s_nop 0
	v_addc_co_u32_e32 v133, vcc, 0, v129, vcc
	global_load_dwordx4 v[222:225], v[130:131], off
	global_load_dwordx4 v[226:229], v[132:133], off
	v_add_co_u32_e32 v130, vcc, s39, v128
	s_mov_b32 s39, 0x10000
	s_nop 0
	v_addc_co_u32_e32 v131, vcc, 0, v129, vcc
	v_add_co_u32_e32 v132, vcc, s29, v128
	s_nop 0
	s_nop 0
	v_addc_co_u32_e32 v133, vcc, 0, v129, vcc
	global_load_dwordx4 v[230:233], v[130:131], off
	global_load_dwordx4 v[234:237], v[132:133], off
	v_add_co_u32_e32 v130, vcc, s39, v128
	s_mov_b32 s39, 0x12000
	s_nop 0
	v_addc_co_u32_e32 v131, vcc, 0, v129, vcc
	v_add_co_u32_e32 v132, vcc, s39, v128
	s_mov_b32 s39, 0x14000
	s_nop 0
	v_addc_co_u32_e32 v133, vcc, 0, v129, vcc
	global_load_dwordx4 v[156:159], v[130:131], off
	global_load_dwordx4 v[152:155], v[132:133], off
	v_add_co_u32_e32 v130, vcc, s39, v128
	s_mov_b32 s39, 0x16000
	s_nop 0
	v_addc_co_u32_e32 v131, vcc, 0, v129, vcc
	v_add_co_u32_e32 v132, vcc, s39, v128
	s_mov_b32 s39, 0x18000
	s_nop 0
	v_addc_co_u32_e32 v133, vcc, 0, v129, vcc
	global_load_dwordx4 v[148:151], v[130:131], off
	global_load_dwordx4 v[144:147], v[132:133], off
	v_add_co_u32_e32 v130, vcc, s39, v128
	s_mov_b32 s39, 0x1a000
	s_nop 0
	v_addc_co_u32_e32 v131, vcc, 0, v129, vcc
	v_add_co_u32_e32 v132, vcc, s39, v128
	s_mov_b32 s39, 0x1c000
	s_nop 0
	v_addc_co_u32_e32 v133, vcc, 0, v129, vcc
	global_load_dwordx4 v[140:143], v[130:131], off
	global_load_dwordx4 v[136:139], v[132:133], off
	v_add_co_u32_e32 v130, vcc, s39, v128
	s_mov_b32 s39, 0x1e000
	s_nop 0
	v_addc_co_u32_e32 v131, vcc, 0, v129, vcc
	v_add_co_u32_e32 v128, vcc, s39, v128
	s_nop 0
	s_nop 0
	v_addc_co_u32_e32 v129, vcc, 0, v129, vcc
	global_load_dwordx4 v[132:135], v[130:131], off
	s_nop 0
	global_load_dwordx4 v[128:131], v[128:129], off
	s_waitcnt vmcnt(0)
	v_lshlrev_b32_e32 v188, 16, v184
	v_and_b32_e32 v189, 0xffff0000, v184
	v_lshlrev_b32_e32 v184, 16, v185
	v_and_b32_e32 v185, 0xffff0000, v185
	v_pk_mul_f32 v[122:123], v[122:123], v[184:185]
	v_lshlrev_b32_e32 v184, 16, v187
	v_and_b32_e32 v185, 0xffff0000, v187
	v_pk_mul_f32 v[126:127], v[126:127], v[184:185]
	v_lshlrev_b32_e32 v184, 16, v210
	v_and_b32_e32 v185, 0xffff0000, v210
	v_pk_mul_f32 v[116:117], v[116:117], v[184:185]
	v_lshlrev_b32_e32 v184, 16, v212
	v_and_b32_e32 v185, 0xffff0000, v212
	v_pk_mul_f32 v[112:113], v[112:113], v[184:185]
	v_lshlrev_b32_e32 v184, 16, v211
	v_and_b32_e32 v185, 0xffff0000, v211
	v_pk_mul_f32 v[118:119], v[118:119], v[184:185]
	v_lshlrev_b32_e32 v184, 16, v213
	v_and_b32_e32 v185, 0xffff0000, v213
	v_pk_mul_f32 v[114:115], v[114:115], v[184:185]
	s_waitcnt vmcnt(0)
; __device__ __forceinline__ void unpack8(const u32x4 w, float (&f)[8]) { f[0] = bflo(w.x); f[1] = bfhi(w.x); f[2] = bflo(w.y); f[3] = bfhi(w.y); f[4] = bflo(w.z); f[5] = bfhi(w.z); f[6] = bflo(w.w); f[7] = bfhi(w.w); }
;     __device__ __forceinline__ void segment(Acc& acc, const Unit& u, int seg, int wr, int wc, int fr, int fq) const {
;     ...
;         for (int ai = 0; ai < 2; ++ai)
; #pragma unroll
;             for (int m = 0; m < 4; ++m)
; #pragma unroll
;                 for (int bj = 0; bj < 2; ++bj) { float r[8]; unpack8(rr[ai][m][bj], r);
; #pragma unroll
;                     for (int e = 0; e < 4; ++e) { acc[ai][bj][m][0][e] *= r[e]; acc[ai][bj][m][1][e] *= r[4 + e]; } }
;         __builtin_amdgcn_sched_barrier(0);
	v_lshlrev_b32_e32 v184, 16, v214
	v_and_b32_e32 v185, 0xffff0000, v214
	v_pk_mul_f32 v[108:109], v[108:109], v[184:185]
	v_lshlrev_b32_e32 v184, 16, v216
	v_and_b32_e32 v185, 0xffff0000, v216
	v_pk_mul_f32 v[104:105], v[104:105], v[184:185]
	v_lshlrev_b32_e32 v184, 16, v215
	v_and_b32_e32 v185, 0xffff0000, v215
	v_pk_mul_f32 v[110:111], v[110:111], v[184:185]
	v_lshlrev_b32_e32 v184, 16, v217
	v_and_b32_e32 v185, 0xffff0000, v217
	v_pk_mul_f32 v[106:107], v[106:107], v[184:185]
	v_lshlrev_b32_e32 v184, 16, v218
	v_and_b32_e32 v185, 0xffff0000, v218
	v_pk_mul_f32 v[100:101], v[100:101], v[184:185]
	v_lshlrev_b32_e32 v184, 16, v220
	v_and_b32_e32 v185, 0xffff0000, v220
	v_pk_mul_f32 v[96:97], v[96:97], v[184:185]
	v_lshlrev_b32_e32 v184, 16, v219
	v_and_b32_e32 v185, 0xffff0000, v219
	v_pk_mul_f32 v[102:103], v[102:103], v[184:185]
	v_lshlrev_b32_e32 v184, 16, v221
	v_and_b32_e32 v185, 0xffff0000, v221
	v_pk_mul_f32 v[98:99], v[98:99], v[184:185]
	v_lshlrev_b32_e32 v184, 16, v222
	v_and_b32_e32 v185, 0xffff0000, v222
	v_pk_mul_f32 v[92:93], v[92:93], v[184:185]
	v_lshlrev_b32_e32 v184, 16, v224
	v_and_b32_e32 v185, 0xffff0000, v224
	v_pk_mul_f32 v[88:89], v[88:89], v[184:185]
	v_lshlrev_b32_e32 v184, 16, v223
	v_and_b32_e32 v185, 0xffff0000, v223
	v_pk_mul_f32 v[94:95], v[94:95], v[184:185]
	v_lshlrev_b32_e32 v184, 16, v225
	v_and_b32_e32 v185, 0xffff0000, v225
	v_pk_mul_f32 v[90:91], v[90:91], v[184:185]
	v_lshlrev_b32_e32 v184, 16, v226
	v_and_b32_e32 v185, 0xffff0000, v226
	v_pk_mul_f32 v[84:85], v[84:85], v[184:185]
	v_lshlrev_b32_e32 v184, 16, v228
	v_and_b32_e32 v185, 0xffff0000, v228
	v_pk_mul_f32 v[80:81], v[80:81], v[184:185]
	v_lshlrev_b32_e32 v184, 16, v227
	v_and_b32_e32 v185, 0xffff0000, v227
	v_pk_mul_f32 v[86:87], v[86:87], v[184:185]
	v_lshlrev_b32_e32 v184, 16, v229
	v_and_b32_e32 v185, 0xffff0000, v229
	v_pk_mul_f32 v[82:83], v[82:83], v[184:185]
	v_lshlrev_b32_e32 v184, 16, v230
	v_and_b32_e32 v185, 0xffff0000, v230
	v_pk_mul_f32 v[76:77], v[76:77], v[184:185]
	v_lshlrev_b32_e32 v184, 16, v232
	v_and_b32_e32 v185, 0xffff0000, v232
	v_pk_mul_f32 v[72:73], v[72:73], v[184:185]
	v_lshlrev_b32_e32 v184, 16, v231
	v_and_b32_e32 v185, 0xffff0000, v231
	v_pk_mul_f32 v[78:79], v[78:79], v[184:185]
	v_lshlrev_b32_e32 v184, 16, v233
	v_and_b32_e32 v185, 0xffff0000, v233
	v_pk_mul_f32 v[74:75], v[74:75], v[184:185]
	v_lshlrev_b32_e32 v184, 16, v234
	v_and_b32_e32 v185, 0xffff0000, v234
	v_pk_mul_f32 v[68:69], v[68:69], v[184:185]
	v_lshlrev_b32_e32 v184, 16, v236
	v_and_b32_e32 v185, 0xffff0000, v236
	v_pk_mul_f32 v[64:65], v[64:65], v[184:185]
	v_lshlrev_b32_e32 v184, 16, v235
	v_and_b32_e32 v185, 0xffff0000, v235
	v_pk_mul_f32 v[70:71], v[70:71], v[184:185]
	v_lshlrev_b32_e32 v184, 16, v237
	v_and_b32_e32 v185, 0xffff0000, v237
	v_pk_mul_f32 v[66:67], v[66:67], v[184:185]
	v_lshlrev_b32_e32 v184, 16, v156
	v_and_b32_e32 v185, 0xffff0000, v156
	v_lshlrev_b32_e32 v156, 16, v157
	v_and_b32_e32 v157, 0xffff0000, v157
	v_pk_mul_f32 v[62:63], v[62:63], v[156:157]
	v_lshlrev_b32_e32 v156, 16, v159
	v_and_b32_e32 v157, 0xffff0000, v159
	v_pk_mul_f32 v[58:59], v[58:59], v[156:157]
	v_lshlrev_b32_e32 v156, 16, v152
	v_and_b32_e32 v157, 0xffff0000, v152
	v_lshlrev_b32_e32 v152, 16, v153
	v_and_b32_e32 v153, 0xffff0000, v153
	v_pk_mul_f32 v[54:55], v[54:55], v[152:153]
	v_lshlrev_b32_e32 v152, 16, v155
	v_and_b32_e32 v153, 0xffff0000, v155
	v_pk_mul_f32 v[50:51], v[50:51], v[152:153]
	v_lshlrev_b32_e32 v152, 16, v148
	v_and_b32_e32 v153, 0xffff0000, v148
	v_lshlrev_b32_e32 v148, 16, v149
	v_and_b32_e32 v149, 0xffff0000, v149
	v_pk_mul_f32 v[46:47], v[46:47], v[148:149]
	v_lshlrev_b32_e32 v148, 16, v151
	v_and_b32_e32 v149, 0xffff0000, v151
	v_pk_mul_f32 v[42:43], v[42:43], v[148:149]
	v_lshlrev_b32_e32 v148, 16, v144
	v_and_b32_e32 v149, 0xffff0000, v144
	v_lshlrev_b32_e32 v144, 16, v145
	v_and_b32_e32 v145, 0xffff0000, v145
	v_pk_mul_f32 v[38:39], v[38:39], v[144:145]
	v_lshlrev_b32_e32 v144, 16, v147
	v_and_b32_e32 v145, 0xffff0000, v147
	v_pk_mul_f32 v[34:35], v[34:35], v[144:145]
	v_lshlrev_b32_e32 v144, 16, v140
	v_and_b32_e32 v145, 0xffff0000, v140
	v_lshlrev_b32_e32 v140, 16, v141
	v_and_b32_e32 v141, 0xffff0000, v141
	v_pk_mul_f32 v[30:31], v[30:31], v[140:141]
	v_lshlrev_b32_e32 v140, 16, v143
	v_and_b32_e32 v141, 0xffff0000, v143
	v_pk_mul_f32 v[26:27], v[26:27], v[140:141]
	v_lshlrev_b32_e32 v140, 16, v136
	v_and_b32_e32 v141, 0xffff0000, v136
	v_lshlrev_b32_e32 v136, 16, v137
	v_and_b32_e32 v137, 0xffff0000, v137
	v_pk_mul_f32 v[22:23], v[22:23], v[136:137]
	v_lshlrev_b32_e32 v136, 16, v139
	v_and_b32_e32 v137, 0xffff0000, v139
	v_pk_mul_f32 v[18:19], v[18:19], v[136:137]
	v_lshlrev_b32_e32 v136, 16, v132
	v_and_b32_e32 v137, 0xffff0000, v132
	v_lshlrev_b32_e32 v132, 16, v133
	v_and_b32_e32 v133, 0xffff0000, v133
	v_pk_mul_f32 v[14:15], v[14:15], v[132:133]
	v_lshlrev_b32_e32 v132, 16, v135
	v_and_b32_e32 v133, 0xffff0000, v135
	v_pk_mul_f32 v[10:11], v[10:11], v[132:133]
	v_lshlrev_b32_e32 v132, 16, v128
	v_and_b32_e32 v133, 0xffff0000, v128
	v_lshlrev_b32_e32 v128, 16, v129
	v_and_b32_e32 v129, 0xffff0000, v129
	v_pk_mul_f32 v[120:121], v[120:121], v[188:189]
	v_lshlrev_b32_e32 v188, 16, v186
	v_and_b32_e32 v189, 0xffff0000, v186
	v_pk_mul_f32 v[60:61], v[60:61], v[184:185]
	v_lshlrev_b32_e32 v184, 16, v158
	v_and_b32_e32 v185, 0xffff0000, v158
	v_pk_mul_f32 v[52:53], v[52:53], v[156:157]
	v_lshlrev_b32_e32 v156, 16, v154
	v_and_b32_e32 v157, 0xffff0000, v154
	v_pk_mul_f32 v[44:45], v[44:45], v[152:153]
	v_lshlrev_b32_e32 v152, 16, v150
	v_and_b32_e32 v153, 0xffff0000, v150
	v_pk_mul_f32 v[36:37], v[36:37], v[148:149]
	v_lshlrev_b32_e32 v148, 16, v146
	v_and_b32_e32 v149, 0xffff0000, v146
	v_pk_mul_f32 v[28:29], v[28:29], v[144:145]
	v_lshlrev_b32_e32 v144, 16, v142
	v_and_b32_e32 v145, 0xffff0000, v142
	v_pk_mul_f32 v[20:21], v[20:21], v[140:141]
	v_lshlrev_b32_e32 v140, 16, v138
	v_and_b32_e32 v141, 0xffff0000, v138
	v_pk_mul_f32 v[12:13], v[12:13], v[136:137]
	v_lshlrev_b32_e32 v136, 16, v134
	v_and_b32_e32 v137, 0xffff0000, v134
	v_pk_mul_f32 v[4:5], v[4:5], v[132:133]
	v_lshlrev_b32_e32 v132, 16, v130
	v_and_b32_e32 v133, 0xffff0000, v130
	v_pk_mul_f32 v[6:7], v[6:7], v[128:129]
	v_lshlrev_b32_e32 v128, 16, v131
	v_and_b32_e32 v129, 0xffff0000, v131
	v_pk_mul_f32 v[124:125], v[124:125], v[188:189]
	v_pk_mul_f32 v[56:57], v[56:57], v[184:185]
	v_pk_mul_f32 v[48:49], v[48:49], v[156:157]
	v_pk_mul_f32 v[40:41], v[40:41], v[152:153]
	v_pk_mul_f32 v[32:33], v[32:33], v[148:149]
	v_pk_mul_f32 v[24:25], v[24:25], v[144:145]
	v_pk_mul_f32 v[16:17], v[16:17], v[140:141]
	v_pk_mul_f32 v[8:9], v[8:9], v[136:137]
	v_pk_mul_f32 v[0:1], v[0:1], v[132:133]
	v_pk_mul_f32 v[2:3], v[2:3], v[128:129]

; __device__ __forceinline__ void prep_layer_jobs(PP p, unsigned char* smem, int layer, int start, int stride, int jlo, int jhi) {
;     for (int j = jlo + start; j < jhi; j += stride) {
; template <int PMASK> __device__ __forceinline__ void run_phase(PP p, int ph, unsigned char* smem) {
;     ...
;     case 6: if constexpr ((PMASK >> 6) & 1) { OrderSimple S{ws + WS_U, ws + WS_WBRT + (size_t)layer * DM * DM * 2, layer == 3 ? 64 : 68, 8, DM, DM, G, c};
;         EpiBranch Ep{(const bf16_t*)(p->ws + WS_R), (bf16_t*)(p->ws + WS_MRG)};
;         pg8::gemm_phase(lds, pg8::Gemm{DM, DM, DM}, S, Ep);
;         if (layer < 3 && c >= 32) { __syncthreads(); prep_layer_jobs(p, smem, layer + 1, c - 32, G - 32, 0, 2544); } } break;
.LBB0_138:
	s_mov_b32 s4, s10
	v_writelane_b32 v249, s4, 63
	s_cmp_gt_i32 s10, 2
	v_readlane_b32 s8, v249, 11
	v_readlane_b32 s9, v249, 12
	s_cselect_b64 s[6:7], -1, 0
	s_xor_b64 s[8:9], s[8:9], -1
	s_or_b64 s[6:7], s[8:9], s[6:7]
	s_and_b64 vcc, exec, s[6:7]
	v_writelane_b32 v248, s5, 0
	s_cbranch_vccnz .LBB0_302
	v_readlane_b32 s6, v249, 15
	v_readlane_b32 s7, v249, 16
	s_andn2_b64 vcc, exec, s[6:7]
	s_waitcnt vmcnt(0) lgkmcnt(0)
	s_barrier
	s_cbranch_vccnz .LBB0_302
	v_readlane_b32 s6, v249, 63
	v_readlane_b32 s7, v248, 0
	s_add_i32 s6, s6, 1
	s_load_dwordx2 s[12:13], s[0:1], 0xd0
	s_ashr_i32 s7, s6, 31
	s_lshl_b64 s[8:9], s[6:7], 21
	v_writelane_b32 v248, s8, 4
	s_lshl_b64 s[16:17], s[6:7], 22
	s_lshl_b32 s47, s6, 7
	v_writelane_b32 v248, s9, 5
	s_lshl_b64 s[8:9], s[6:7], 20
	s_lshl_b32 s48, s6, 5
	s_waitcnt lgkmcnt(0)
	s_add_u32 s8, s12, s8
	s_addc_u32 s9, s13, s9
	s_add_u32 s46, s8, 0x12000000
	s_mul_hi_i32 s42, s6, 0x7000000
	s_mul_i32 s43, s6, 0x7000000
	s_mul_hi_i32 s4, s6, 0x3800000
	s_mul_i32 s10, s6, 0x3800000
	s_mul_i32 s49, s6, 48
	s_addc_u32 s8, s9, 0
	s_lshl_b64 s[6:7], s[6:7], 23
	v_writelane_b32 v248, s8, 3
	s_add_u32 s8, s12, s6
	s_addc_u32 s9, s13, s7
	s_add_u32 s8, s8, 0x10000000
	v_writelane_b32 v248, s8, 6
	s_addc_u32 s8, s9, 0
	s_add_u32 s61, s14, s6
	s_addc_u32 s62, s15, s7
	s_add_u32 s63, s12, s10
	s_addc_u32 s64, s13, s4
	s_add_u32 s18, s12, 0x15400000
	s_addc_u32 s19, s13, 0
	s_add_u32 s65, s12, 0x12400000
	s_addc_u32 s50, s13, 0
	s_add_u32 s51, s12, 0x14400000
	s_addc_u32 s55, s13, 0
	s_add_u32 s60, s12, 0x15420000
	s_addc_u32 s14, s13, 0
	v_readlane_b32 s15, v249, 14
	v_writelane_b32 v248, s8, 7
	v_readlane_b32 s4, v248, 62
	s_cmp_lg_u32 s4, 0
	s_cbranch_scc1 .Lprepb_part2_init
	s_cmpk_lt_i32 s15, 0xd0
	s_cbranch_scc1 .LBB0_142
	s_addk_i32 s15, 0xb0
	s_branch .LBB0_142

; __device__ __forceinline__ void prep_layer_jobs(PP p, unsigned char* smem, int layer, int start, int stride, int jlo, int jhi) {
;     for (int j = jlo + start; j < jhi; j += stride) {
;         if (j < 48) job_mod(p, smem, layer * 48 + j);
;         else if (j < 80) job_ssm(p, smem, layer * 32 + (j - 48));
;         else if (j < 208) job_fold(p, smem, layer * 128 + (j - 80));
;         else if (j < 2000) { const int rem = j - 208, rt = rem / 56, ct = rem % 56; if (ct == 8 || ct == 9) continue;
.Lprepb_p2_rank_lo:
	s_addk_i32 s15, 0x550
	s_branch .Lprepb_check

; __device__ __forceinline__ void prep_layer_jobs(PP p, unsigned char* smem, int layer, int start, int stride, int jlo, int jhi) {
;     for (int j = jlo + start; j < jhi; j += stride) {
;         if (j < 48) job_mod(p, smem, layer * 48 + j);
.Lprepb_check:
	v_readlane_b32 s4, v248, 62
	s_cmp_lg_u32 s4, 0
	s_movk_i32 s4, 0x550
	s_cselect_b32 s4, 0x9f0, s4
	s_cmp_ge_i32 s15, s4
	s_cbranch_scc1 .LBB0_302

; template <int PMASK> __device__ __forceinline__ void run_phase(PP p, int ph, unsigned char* smem) {
;     ...
;         if (layer < 3 && c >= 32) { __syncthreads(); prep_layer_jobs(p, smem, layer + 1, c - 32, G - 32, 0, 2544); } } break;
;     case 7: if constexpr ((PMASK >> 7) & 1) { OrderSimple S{ws + WS_MRG, ws + WS_WOT + (size_t)layer * DM * DM * 2, layer == 3 ? 64 : 68, 8, DM, DM, G, c};
;         EpiWo Ep{(bf16_t*)(p->ws + WS_Y)};
;         pg8::gemm_phase(lds, pg8::Gemm{DM, DM, DM}, S, Ep);
;         if (layer < 3 && c >= 32) { __syncthreads(); prep_layer_jobs(p, smem, layer + 1, c - 32, G - 32, 2544, 2544); } } break;
;     }
.LBB0_302:
	s_mov_b32 s46, 0
	s_nop 0
	v_writelane_b32 v248, s46, 62
	v_readlane_b32 s46, v249, 58
	v_readlane_b32 s48, v249, 60
	s_mov_b64 s[6:7], 0
	v_readlane_b32 s47, v249, 59
	v_readlane_b32 s49, v249, 61
	v_readlane_b32 s65, v248, 9
	s_movk_i32 s63, 0x800
	s_mov_b32 s64, 0x800000

; __device__ __forceinline__ bf16_t f2bf(float f) { unsigned u = __float_as_uint(f); u += 0x7FFFu + ((u >> 16) & 1u); return (bf16_t)(u >> 16); }
; __device__ __forceinline__ float bf2f(bf16_t b) { return __uint_as_float(((unsigned)b) << 16); }
; __device__ void attn_phase(PP p, int layer) {
;     ...
;         float ltot = lrun + __shfl_xor(lrun, 16); ltot += __shfl_xor(ltot, 32);
;         const float inv = 1.0f / ltot;
; #pragma unroll
;         for (int jj = 0; jj < 4; ++jj) { const float ij = __shfl(inv, quad * 4 + jj); const int tok = tq0 + quad * 4 + jj;
; #pragma unroll
;             for (int dt = 0; dt < 4; ++dt) { const int d = dt * 16 + qi; const float z = bf2f(PROJ[(size_t)tok * NIN + 1536 + head * 64 + d]);
;                 U[(size_t)tok * DM + head * 64 + d] = f2bf(O[dt][jj] * ij * z); } }
;     }
.LBB0_360:
	s_or_b64 exec, exec, s[62:63]
	ds_bpermute_b32 v16, v99, v24
	v_lshlrev_b32_e32 v162, 1, v98
	s_waitcnt lgkmcnt(0)
	v_add_f32_e32 v16, v24, v16
	ds_bpermute_b32 v17, v138, v16
	s_waitcnt lgkmcnt(0)
	v_add_f32_e32 v16, v16, v17
	v_div_scale_f32 v17, s[6:7], v16, v16, 1.0
	v_rcp_f32_e32 v18, v17
	s_nop 0
	v_fma_f32 v19, -v17, v18, 1.0
	v_fmac_f32_e32 v18, v19, v18
	v_div_scale_f32 v19, vcc, 1.0, v16, 1.0
	v_mul_f32_e32 v20, v19, v18
	v_fma_f32 v21, -v17, v20, v19
	v_fmac_f32_e32 v20, v21, v18
	v_fma_f32 v17, -v17, v20, v19
	v_div_fmas_f32 v17, v17, v18, v20
	v_add_u32_e32 v20, v97, v139
	v_lshl_add_u64 v[18:19], s[64:65], 0, v[162:163]
	v_mad_i64_i32 v[22:23], s[6:7], v20, s68, v[18:19]
	v_mov_b32_e32 v97, v163
	v_ashrrev_i32_e32 v21, 31, v20
	v_lshl_add_u64 v[22:23], v[22:23], 0, v[96:97]
	v_lshlrev_b64 v[24:25], 12, v[20:21]
	global_load_ushort v210, v[22:23], off offset:3072
	global_load_ushort v211, v[22:23], off offset:3104
	global_load_ushort v212, v[22:23], off offset:3136
	global_load_ushort v213, v[22:23], off offset:3168
	s_mov_b64 s[6:7], 0x7000
	s_nop 0
	v_lshl_add_u64 v[226:227], v[22:23], 0, s[6:7]
	global_load_ushort v214, v[226:227], off offset:3072
	global_load_ushort v215, v[226:227], off offset:3104
	global_load_ushort v216, v[226:227], off offset:3136
	global_load_ushort v217, v[226:227], off offset:3168
	s_mov_b64 s[6:7], 0xe000
	s_nop 0
	v_lshl_add_u64 v[226:227], v[22:23], 0, s[6:7]
	global_load_ushort v218, v[226:227], off offset:3072
	global_load_ushort v219, v[226:227], off offset:3104
	global_load_ushort v220, v[226:227], off offset:3136
	global_load_ushort v221, v[226:227], off offset:3168
	s_mov_b64 s[6:7], 0x15000
	s_nop 0
	v_lshl_add_u64 v[226:227], v[22:23], 0, s[6:7]
	global_load_ushort v222, v[226:227], off offset:3072
	global_load_ushort v223, v[226:227], off offset:3104
	global_load_ushort v224, v[226:227], off offset:3136
	global_load_ushort v225, v[226:227], off offset:3168
	v_div_fixup_f32 v26, v17, v16, 1.0
	ds_bpermute_b32 v27, v140, v26
	v_lshl_add_u64 v[16:17], s[48:49], 0, v[162:163]
	v_lshl_add_u64 v[24:25], v[16:17], 0, v[24:25]
	v_lshl_add_u64 v[24:25], v[24:25], 0, v[96:97]
	s_waitcnt lgkmcnt(0)
	v_mul_f32_e32 v12, v12, v27
	v_mul_f32_e32 v8, v8, v27
	v_mul_f32_e32 v4, v4, v27
	v_mul_f32_e32 v0, v0, v27
	s_waitcnt vmcnt(0)
	v_mov_b32_e32 v21, v210
	v_lshlrev_b32_e32 v21, 16, v21
	v_mul_f32_e32 v12, v12, v21
	v_bfe_u32 v21, v12, 16, 1
	v_add3_u32 v12, v12, v21, s69
	global_store_short_d16_hi v[24:25], v12, off
	v_mov_b32_e32 v12, v211
	s_nop 0
	v_lshlrev_b32_e32 v12, 16, v12
	v_mul_f32_e32 v8, v8, v12
	v_bfe_u32 v12, v8, 16, 1
	v_add3_u32 v8, v8, v12, s69
	global_store_short_d16_hi v[24:25], v8, off offset:32
	v_mov_b32_e32 v8, v212
	s_nop 0
	v_lshlrev_b32_e32 v8, 16, v8
	v_mul_f32_e32 v4, v4, v8
	v_bfe_u32 v8, v4, 16, 1
	v_add3_u32 v4, v4, v8, s69
	global_store_short_d16_hi v[24:25], v4, off offset:64
	v_mov_b32_e32 v4, v213
	v_add_u32_e32 v22, 1, v20
	v_ashrrev_i32_e32 v23, 31, v22
	s_nop 0
	v_lshlrev_b32_e32 v4, 16, v4
	v_mul_f32_e32 v0, v0, v4
	v_bfe_u32 v4, v0, 16, 1
	v_add3_u32 v0, v0, v4, s69
	global_store_short_d16_hi v[24:25], v0, off offset:96
	v_mad_i64_i32 v[24:25], s[6:7], v22, s68, v[18:19]
	v_lshl_add_u64 v[24:25], v[24:25], 0, v[96:97]
	v_mov_b32_e32 v4, v214
	ds_bpermute_b32 v0, v141, v26
	v_lshlrev_b64 v[22:23], 12, v[22:23]
	v_lshl_add_u64 v[22:23], v[16:17], 0, v[22:23]
	s_waitcnt lgkmcnt(0)
	v_mul_f32_e32 v8, v13, v0
	v_lshl_add_u64 v[12:13], v[22:23], 0, v[96:97]
	v_mul_f32_e32 v5, v5, v0
	s_nop 0
	v_lshlrev_b32_e32 v4, 16, v4
	v_mul_f32_e32 v4, v8, v4
	v_bfe_u32 v8, v4, 16, 1
	v_add3_u32 v4, v4, v8, s69
	global_store_short_d16_hi v[12:13], v4, off
	v_mov_b32_e32 v4, v215
	v_mul_f32_e32 v8, v9, v0
	v_mul_f32_e32 v0, v1, v0
	s_nop 0
	v_lshlrev_b32_e32 v4, 16, v4
	v_mul_f32_e32 v4, v8, v4
	v_bfe_u32 v8, v4, 16, 1
	v_add3_u32 v4, v4, v8, s69
	global_store_short_d16_hi v[12:13], v4, off offset:32
	v_mov_b32_e32 v4, v216
	ds_bpermute_b32 v8, v142, v26
	s_waitcnt lgkmcnt(0)
	v_mul_f32_e32 v10, v10, v8
	v_mul_f32_e32 v6, v6, v8
	v_mul_f32_e32 v2, v2, v8
	s_nop 0
	v_lshlrev_b32_e32 v4, 16, v4
	v_mul_f32_e32 v4, v5, v4
	v_bfe_u32 v5, v4, 16, 1
	v_add3_u32 v4, v4, v5, s69
	global_store_short_d16_hi v[12:13], v4, off offset:64
	v_mov_b32_e32 v4, v217
	s_nop 0
	v_lshlrev_b32_e32 v4, 16, v4
	v_mul_f32_e32 v0, v0, v4
	v_bfe_u32 v1, v0, 16, 1
	v_add3_u32 v0, v0, v1, s69
	global_store_short_d16_hi v[12:13], v0, off offset:96
	v_add_u32_e32 v0, 2, v20
	v_mad_i64_i32 v[4:5], s[6:7], v0, s68, v[18:19]
	v_lshl_add_u64 v[4:5], v[4:5], 0, v[96:97]
	v_mov_b32_e32 v9, v218
	v_ashrrev_i32_e32 v1, 31, v0
	v_mul_f32_e32 v12, v14, v8
	v_lshlrev_b64 v[0:1], 12, v[0:1]
	v_lshl_add_u64 v[0:1], v[16:17], 0, v[0:1]
	v_lshl_add_u64 v[0:1], v[0:1], 0, v[96:97]
	s_nop 0
	v_lshlrev_b32_e32 v9, 16, v9
	v_mul_f32_e32 v9, v12, v9
	v_bfe_u32 v12, v9, 16, 1
	v_add3_u32 v9, v9, v12, s69
	global_store_short_d16_hi v[0:1], v9, off
	v_mov_b32_e32 v9, v219
	s_nop 0
	v_lshlrev_b32_e32 v9, 16, v9
	v_mul_f32_e32 v9, v10, v9
	v_bfe_u32 v10, v9, 16, 1
	v_add3_u32 v9, v9, v10, s69
	global_store_short_d16_hi v[0:1], v9, off offset:32
	v_mov_b32_e32 v9, v220
	s_nop 0
	v_lshlrev_b32_e32 v9, 16, v9
	v_mov_b32_e32 v4, v221
	v_mul_f32_e32 v6, v6, v9
	v_bfe_u32 v9, v6, 16, 1
	v_add3_u32 v6, v6, v9, s69
	global_store_short_d16_hi v[0:1], v6, off offset:64
	s_nop 0
	v_lshlrev_b32_e32 v4, 16, v4
	v_mul_f32_e32 v2, v2, v4
	v_bfe_u32 v4, v2, 16, 1
	v_add3_u32 v2, v2, v4, s69
	global_store_short_d16_hi v[0:1], v2, off offset:96
	v_add_u32_e32 v0, 3, v20
	v_mad_i64_i32 v[4:5], s[6:7], v0, s68, v[18:19]
	v_lshl_add_u64 v[4:5], v[4:5], 0, v[96:97]
	v_mov_b32_e32 v6, v222
	ds_bpermute_b32 v2, v143, v26
	v_ashrrev_i32_e32 v1, 31, v0
	v_lshlrev_b64 v[0:1], 12, v[0:1]
	v_lshl_add_u64 v[0:1], v[16:17], 0, v[0:1]
	v_lshl_add_u64 v[0:1], v[0:1], 0, v[96:97]
	s_waitcnt lgkmcnt(0)
	v_mul_f32_e32 v8, v15, v2
	v_mul_f32_e32 v7, v7, v2
	v_readlane_b32 s6, v249, 26
	s_nop 0
	v_lshlrev_b32_e32 v6, 16, v6
	v_mul_f32_e32 v6, v8, v6
	v_bfe_u32 v8, v6, 16, 1
	v_add3_u32 v6, v6, v8, s69
	global_store_short_d16_hi v[0:1], v6, off
	v_mov_b32_e32 v6, v223
	v_mul_f32_e32 v8, v11, v2
	v_mul_f32_e32 v2, v3, v2
	v_add_u32_e32 v89, s6, v89
	v_cmp_le_i32_e32 vcc, s4, v89
	s_or_b64 s[60:61], vcc, s[60:61]
	s_nop 0
	v_lshlrev_b32_e32 v6, 16, v6
	v_mul_f32_e32 v6, v8, v6
	v_bfe_u32 v8, v6, 16, 1
	v_add3_u32 v6, v6, v8, s69
	global_store_short_d16_hi v[0:1], v6, off offset:32
	v_mov_b32_e32 v6, v224
	s_nop 0
	v_lshlrev_b32_e32 v6, 16, v6
	v_mov_b32_e32 v4, v225
	v_mul_f32_e32 v6, v7, v6
	v_bfe_u32 v7, v6, 16, 1
	v_add3_u32 v6, v6, v7, s69
	global_store_short_d16_hi v[0:1], v6, off offset:64
	s_nop 0
	v_lshlrev_b32_e32 v4, 16, v4
	v_mul_f32_e32 v2, v2, v4
	v_bfe_u32 v3, v2, 16, 1
	v_add3_u32 v2, v2, v3, s69
	global_store_short_d16_hi v[0:1], v2, off offset:96
	s_andn2_b64 exec, exec, s[60:61]
	s_cbranch_execz .LBB0_403
